# v095 + P1 K-loop load segments: LDS-DMA stage loads (address math, m0, global_load_lds) issued at the segment start ahead of the fragment ds_reads
# baseline (speedup 1.0000x reference)
; #define PG8_LAS __attribute__((address_space(3)))
; #define PG8_STAGE(bufoff, gbase, voff) do { _Pragma("unroll") for (int _i = 0; _i < 2; ++_i) \
;         __builtin_amdgcn_global_load_lds((const unsigned*)((const char*)(gbase) + (voff)[_i]), (PG8_LAS unsigned*)(lds + (bufoff) + ldsw + _i * 8192), 16, 0, 0); } while (0)
; #define PG8_WAIT_V(n) asm volatile("s_waitcnt vmcnt(" #n ")" ::: "memory")
; #define PG8_BAR __builtin_amdgcn_s_barrier()
; template <class Epi, class Sched, bool ALIGN_EPI = false, bool SP2 = false, bool RS = false, bool BPRE = false>
; __device__ __forceinline__ void gemm_phase(PG8_LAS unsigned char* lds, const Gemm g, const Sched& S, const Epi& E, const float* rs_ss = nullptr, PG8_LAS float* rs_tab = nullptr) {
;     ...
;         const bool has_next = S.next(ui + 1, nxt);
;         const char* nA = has_next ? (const char*)g.A + (size_t)nxt.pm * tstep : cA; const char* nB = has_next ? (const char*)g.Bt + (size_t)nxt.pn * tstep : cB;
;         for (int t = 0; t < nt; t += 2) {
;             const bool last = (t == nt - 2);
;             if constexpr (RS) { if (t == 16 || t == 32) { const PG8_LAS float* tp = rs_tab + (ui & 1) * 768 + (t == 32 ? 256 : 0);
;                 _Pragma("unroll") for (int a = 0; a < 2; ++a) _Pragma("unroll") for (int m = 0; m < 4; ++m) { const float f = tp[a * HALF + wr * 64 + m * 16 + fr];
;                     _Pragma("unroll") for (int b = 0; b < 2; ++b) _Pragma("unroll") for (int n = 0; n < 2; ++n) acc[a][b][m][n] = acc[a][b][m][n] * f; } } }
;             const char* a1 = cA + (size_t)(t + 1) * kstep;
;             const char* a2 = last ? nA : cA + (size_t)(t + 2) * kstep; const char* b2 = last ? nB : cB + (size_t)(t + 2) * kstep;
;             const char* a3 = a2 + kstep; const char* b3 = b2 + kstep;
;             if (last && has_next) S.a_ready(nxt);
;             if constexpr (SP2) {
;             PG8_LDB(B0, 0, 0); PG8_LDB(B1, 0, 1); PG8_SCHED; PG8_LDA(At, 0, 0); PG8_STAGE(PG8_SA(1, 1), a1 + hstep, voffA);
;             PG8_WAIT_V(8); PG8_WAIT_L(0); PG8_BAR; PG8_MMA(0, 0, At, B0); PG8_MMA(0, 1, At, B1); PG8_BAR; PG8_SCHED;
;             PG8_LDA(At, 0, 1); PG8_STAGE(PG8_SB(0, 0), b2, voffB); PG8_STAGE(PG8_SB(0, 1), b2 + hstep, voffB); PG8_STAGE(PG8_SA(0, 0), a2, voffA);
;             PG8_WAIT_V(8); PG8_WAIT_L(0); PG8_BAR; PG8_MMA(1, 0, At, B0); PG8_MMA(1, 1, At, B1); PG8_BAR; PG8_SCHED;
.LBB0_195:
	s_ashr_i32 s19, s18, 31
	s_lshl_b64 s[20:21], s[18:19], 20
	s_add_u32 s20, s30, s20
	s_addc_u32 s21, s31, s21
	s_and_b64 s[44:45], s[6:7], exec
	s_cselect_b32 s5, s21, s57
	s_cselect_b32 s19, s20, s56
	s_ashr_i32 s17, s16, 31
	s_lshl_b64 s[44:45], s[16:17], 20
	s_add_u32 s44, s24, s44
	s_addc_u32 s45, s25, s45
	s_and_b64 s[60:61], s[6:7], exec
	s_cselect_b32 s17, s45, s59
	s_cselect_b32 s47, s44, s58
	s_add_u32 s56, s56, 0x84000
	s_addc_u32 s57, s57, 0
	s_add_u32 s87, s58, 0x8000
	s_addc_u32 s88, s59, 0
	s_mov_b32 s89, -2
	s_waitcnt lgkmcnt(0)
	s_add_u32 s58, s56, 0xfff84000
	s_addc_u32 s59, s57, -1
	s_cmp_eq_u32 s89, 28
	s_cselect_b32 s70, s19, s58
	s_cselect_b32 s71, s5, s59
	s_cselect_b32 s60, s47, s87
	s_cselect_b32 s61, s17, s88
	s_add_u32 s58, s70, 0x4000
	s_addc_u32 s59, s71, 0
	v_lshl_add_u64 v[178:179], s[56:57], 0, v[138:139]
	s_add_i32 m0, s72, 0xc000
	s_nop 0
	global_load_lds_dwordx4 v[178:179], off
	v_lshl_add_u64 v[178:179], s[56:57], 0, v[146:147]
	s_add_i32 m0, s72, 0xe000
	s_nop 0
	global_load_lds_dwordx4 v[178:179], off
	ds_read_b128 v[130:133], v161
	ds_read_b128 v[134:137], v161 offset:1024
	ds_read_b128 v[152:155], v161 offset:2048
	ds_read_b128 v[156:159], v161 offset:3072
	ds_read_b128 v[166:169], v162
	ds_read_b128 v[170:173], v162 offset:1024
	ds_read_b128 v[174:177], v162 offset:2048
	ds_read_b128 v[182:185], v162 offset:3072
	ds_read_b128 v[188:191], v163
	ds_read_b128 v[192:195], v163 offset:1024
	ds_read_b128 v[196:199], v163 offset:2048
	ds_read_b128 v[200:203], v163 offset:3072
	ds_read_b128 v[204:207], v163 offset:4096
	ds_read_b128 v[208:211], v163 offset:5120
	ds_read_b128 v[212:215], v163 offset:6144
	ds_read_b128 v[216:219], v163 offset:7168
	s_waitcnt vmcnt(8)
	s_waitcnt lgkmcnt(0)
	s_barrier
	s_setprio 1
	s_waitcnt lgkmcnt(0)
	v_mfma_f32_16x16x32_bf16 v[126:129], v[130:133], v[188:191], 0
	v_mfma_f32_16x16x32_bf16 v[126:129], v[134:137], v[192:195], v[126:129]
	v_mfma_f32_16x16x32_bf16 v[122:125], v[156:159], v[192:195], 0
	v_mfma_f32_16x16x32_bf16 v[122:125], v[152:155], v[188:191], v[122:125]
	v_mfma_f32_16x16x32_bf16 v[106:109], v[152:155], v[196:199], 0
	v_mfma_f32_16x16x32_bf16 v[106:109], v[156:159], v[200:203], v[106:109]
	v_mfma_f32_16x16x32_bf16 v[110:113], v[134:137], v[200:203], 0
	v_mfma_f32_16x16x32_bf16 v[110:113], v[130:133], v[196:199], v[110:113]
	v_mfma_f32_16x16x32_bf16 v[94:97], v[130:133], v[204:207], 0
	v_mfma_f32_16x16x32_bf16 v[94:97], v[134:137], v[208:211], v[94:97]
	v_mfma_f32_16x16x32_bf16 v[90:93], v[156:159], v[208:211], 0
	v_mfma_f32_16x16x32_bf16 v[90:93], v[152:155], v[204:207], v[90:93]
	v_mfma_f32_16x16x32_bf16 v[74:77], v[152:155], v[212:215], 0
	v_mfma_f32_16x16x32_bf16 v[74:77], v[156:159], v[216:219], v[74:77]
	v_mfma_f32_16x16x32_bf16 v[78:81], v[134:137], v[216:219], 0
	v_mfma_f32_16x16x32_bf16 v[78:81], v[130:133], v[212:215], v[78:81]
	s_setprio 0
	s_setprio 1
	v_mfma_f32_16x16x32_bf16 v[70:73], v[166:169], v[212:215], 0
	v_mfma_f32_16x16x32_bf16 v[70:73], v[170:173], v[216:219], v[70:73]
	v_mfma_f32_16x16x32_bf16 v[66:69], v[182:185], v[216:219], 0
	v_mfma_f32_16x16x32_bf16 v[66:69], v[174:177], v[212:215], v[66:69]
	v_mfma_f32_16x16x32_bf16 v[82:85], v[174:177], v[204:207], 0
	v_mfma_f32_16x16x32_bf16 v[82:85], v[182:185], v[208:211], v[82:85]
	v_mfma_f32_16x16x32_bf16 v[86:89], v[170:173], v[208:211], 0
	v_mfma_f32_16x16x32_bf16 v[86:89], v[166:169], v[204:207], v[86:89]
	v_mfma_f32_16x16x32_bf16 v[102:105], v[166:169], v[196:199], 0
	v_mfma_f32_16x16x32_bf16 v[102:105], v[170:173], v[200:203], v[102:105]
	v_mfma_f32_16x16x32_bf16 v[98:101], v[182:185], v[200:203], 0
	v_mfma_f32_16x16x32_bf16 v[98:101], v[174:177], v[196:199], v[98:101]
	v_mfma_f32_16x16x32_bf16 v[114:117], v[174:177], v[188:191], 0
	v_mfma_f32_16x16x32_bf16 v[114:117], v[182:185], v[192:195], v[114:117]
	v_mfma_f32_16x16x32_bf16 v[118:121], v[170:173], v[192:195], 0
	v_mfma_f32_16x16x32_bf16 v[118:121], v[166:169], v[188:191], v[118:121]
	s_setprio 0
	s_barrier
	s_add_i32 s90, s83, s15
	v_lshl_add_u64 v[178:179], s[60:61], 0, v[138:139]
	s_mov_b32 m0, s90
	s_nop 0
	global_load_lds_dwordx4 v[178:179], off
	s_add_i32 m0, s90, 0x2000
	s_add_u32 s90, s60, 0x80000
	v_lshl_add_u64 v[178:179], s[60:61], 0, v[140:141]
	s_addc_u32 s91, s61, 0
	s_add_i32 s92, s86, s15
	global_load_lds_dwordx4 v[178:179], off
	v_lshl_add_u64 v[178:179], s[90:91], 0, v[138:139]
	s_mov_b32 m0, s92
	s_nop 0
	global_load_lds_dwordx4 v[178:179], off
	v_lshl_add_u64 v[178:179], s[90:91], 0, v[140:141]
	s_add_i32 m0, s92, 0x2000
	s_nop 0
	global_load_lds_dwordx4 v[178:179], off
	v_lshl_add_u64 v[178:179], s[70:71], 0, v[138:139]
	s_mov_b32 m0, s72
	s_nop 0
	global_load_lds_dwordx4 v[178:179], off
	v_lshl_add_u64 v[178:179], s[70:71], 0, v[140:141]
	s_mov_b32 m0, s73
	s_nop 0
	global_load_lds_dwordx4 v[178:179], off
	ds_read_b128 v[188:191], v163 offset:16384
	ds_read_b128 v[192:195], v163 offset:17408
	ds_read_b128 v[196:199], v163 offset:18432
	ds_read_b128 v[200:203], v163 offset:19456
	ds_read_b128 v[204:207], v163 offset:20480
	ds_read_b128 v[208:211], v163 offset:21504
	ds_read_b128 v[212:215], v163 offset:22528
	ds_read_b128 v[216:219], v163 offset:23552
	s_waitcnt vmcnt(8)
	s_waitcnt lgkmcnt(0)
	s_barrier
; #define PG8_STAGE(bufoff, gbase, voff) do { _Pragma("unroll") for (int _i = 0; _i < 2; ++_i) \
;         __builtin_amdgcn_global_load_lds((const unsigned*)((const char*)(gbase) + (voff)[_i]), (PG8_LAS unsigned*)(lds + (bufoff) + ldsw + _i * 8192), 16, 0, 0); } while (0)
; #define PG8_LDA(dst, b, h) do { _Pragma("unroll") for (int m = 0; m < 4; ++m) _Pragma("unroll") for (int k = 0; k < 2; ++k) dst[m][k] = *(const PG8_LAS bf16x8*)(lds + PG8_SA(b, h) + aoff + m * 2048 + k * 1024); } while (0)
; #define PG8_LDB(dst, b, h) do { _Pragma("unroll") for (int n = 0; n < 2; ++n) _Pragma("unroll") for (int k = 0; k < 2; ++k) dst[n][k] = *(const PG8_LAS bf16x8*)(lds + PG8_SB(b, h) + boff + n * 2048 + k * 1024); } while (0)
; #define PG8_MMA(ai, bj, At, Bt) do { __builtin_amdgcn_s_setprio(1); _Pragma("unroll") for (int m = 0; m < 4; ++m) _Pragma("unroll") for (int n = 0; n < 2; ++n) _Pragma("unroll") for (int k = 0; k < 2; ++k) \
;         acc[ai][bj][m][n] = __builtin_amdgcn_mfma_f32_16x16x32_bf16(Bt[n][k], At[m][k], acc[ai][bj][m][n], 0, 0, 0); __builtin_amdgcn_s_setprio(0); } while (0)
; #define PG8_WAIT_V(n) asm volatile("s_waitcnt vmcnt(" #n ")" ::: "memory")
; #define PG8_WAIT_L(n) asm volatile("s_waitcnt lgkmcnt(" #n ")" ::: "memory")
; #define PG8_BAR __builtin_amdgcn_s_barrier()
; #define PG8_SCHED __builtin_amdgcn_sched_barrier(0)
; template <class Epi, class Sched, bool ALIGN_EPI = false, bool SP2 = false, bool RS = false, bool BPRE = false>
; __device__ __forceinline__ void gemm_phase(PG8_LAS unsigned char* lds, const Gemm g, const Sched& S, const Epi& E, const float* rs_ss = nullptr, PG8_LAS float* rs_tab = nullptr) {
;     ...
;             PG8_WAIT_V(8); PG8_WAIT_L(0); PG8_BAR; PG8_MMA(1, 0, At, B0); PG8_MMA(1, 1, At, B1); PG8_BAR; PG8_SCHED;
;             PG8_LDB(B0, 1, 0); PG8_LDB(B1, 1, 1); PG8_SCHED; PG8_LDA(At, 1, 0); PG8_STAGE(PG8_SA(0, 1), a2 + hstep, voffA);
;             PG8_WAIT_V(8); PG8_WAIT_L(0); PG8_BAR; PG8_MMA(0, 0, At, B0); PG8_MMA(0, 1, At, B1); PG8_BAR; PG8_SCHED;
;             PG8_LDA(At, 1, 1); PG8_STAGE(PG8_SB(1, 0), b3, voffB); PG8_STAGE(PG8_SB(1, 1), b3 + hstep, voffB); PG8_STAGE(PG8_SA(1, 0), a3, voffA);
;             PG8_WAIT_V(8); PG8_WAIT_L(0); PG8_BAR; PG8_MMA(1, 0, At, B0); PG8_MMA(1, 1, At, B1); PG8_BAR; PG8_SCHED;
	s_setprio 1
	s_waitcnt lgkmcnt(0)
	v_mfma_f32_16x16x32_bf16 v[62:65], v[130:133], v[188:191], 0
	v_mfma_f32_16x16x32_bf16 v[62:65], v[134:137], v[192:195], v[62:65]
	v_mfma_f32_16x16x32_bf16 v[58:61], v[156:159], v[192:195], 0
	v_mfma_f32_16x16x32_bf16 v[58:61], v[152:155], v[188:191], v[58:61]
	v_mfma_f32_16x16x32_bf16 v[42:45], v[152:155], v[196:199], 0
	v_mfma_f32_16x16x32_bf16 v[42:45], v[156:159], v[200:203], v[42:45]
	v_mfma_f32_16x16x32_bf16 v[46:49], v[134:137], v[200:203], 0
	v_mfma_f32_16x16x32_bf16 v[46:49], v[130:133], v[196:199], v[46:49]
	v_mfma_f32_16x16x32_bf16 v[30:33], v[130:133], v[204:207], 0
	v_mfma_f32_16x16x32_bf16 v[30:33], v[134:137], v[208:211], v[30:33]
	v_mfma_f32_16x16x32_bf16 v[26:29], v[156:159], v[208:211], 0
	v_mfma_f32_16x16x32_bf16 v[26:29], v[152:155], v[204:207], v[26:29]
	v_mfma_f32_16x16x32_bf16 v[10:13], v[152:155], v[212:215], 0
	v_mfma_f32_16x16x32_bf16 v[10:13], v[156:159], v[216:219], v[10:13]
	v_mfma_f32_16x16x32_bf16 v[14:17], v[134:137], v[216:219], 0
	v_mfma_f32_16x16x32_bf16 v[14:17], v[130:133], v[212:215], v[14:17]
	s_setprio 0
	s_setprio 1
	v_mfma_f32_16x16x32_bf16 v[6:9], v[166:169], v[212:215], 0
	v_mfma_f32_16x16x32_bf16 v[6:9], v[170:173], v[216:219], v[6:9]
	v_mfma_f32_16x16x32_bf16 v[2:5], v[182:185], v[216:219], 0
	v_mfma_f32_16x16x32_bf16 v[2:5], v[174:177], v[212:215], v[2:5]
	v_mfma_f32_16x16x32_bf16 v[18:21], v[174:177], v[204:207], 0
	v_mfma_f32_16x16x32_bf16 v[18:21], v[182:185], v[208:211], v[18:21]
	v_mfma_f32_16x16x32_bf16 v[22:25], v[170:173], v[208:211], 0
	v_mfma_f32_16x16x32_bf16 v[22:25], v[166:169], v[204:207], v[22:25]
	v_mfma_f32_16x16x32_bf16 v[38:41], v[166:169], v[196:199], 0
	v_mfma_f32_16x16x32_bf16 v[38:41], v[170:173], v[200:203], v[38:41]
	v_mfma_f32_16x16x32_bf16 v[34:37], v[182:185], v[200:203], 0
	v_mfma_f32_16x16x32_bf16 v[34:37], v[174:177], v[196:199], v[34:37]
	v_mfma_f32_16x16x32_bf16 v[50:53], v[174:177], v[188:191], 0
	v_mfma_f32_16x16x32_bf16 v[50:53], v[182:185], v[192:195], v[50:53]
	v_mfma_f32_16x16x32_bf16 v[54:57], v[170:173], v[192:195], 0
	v_mfma_f32_16x16x32_bf16 v[54:57], v[166:169], v[188:191], v[54:57]
	s_setprio 0
	s_barrier
	s_add_u32 s70, s70, 0x80000
	s_addc_u32 s71, s71, 0
	s_mov_b32 m0, s74
	v_lshl_add_u64 v[178:179], s[70:71], 0, v[138:139]
	global_load_lds_dwordx4 v[178:179], off
	v_lshl_add_u64 v[178:179], s[70:71], 0, v[140:141]
	s_mov_b32 m0, s75
	s_nop 0
	global_load_lds_dwordx4 v[178:179], off
	s_add_i32 s90, 0, 0x18000
	v_add_u32_e32 v143, s90, v160
	s_add_i32 s91, 0, 0x1c000
	ds_read_b128 v[130:133], v143
	ds_read_b128 v[134:137], v143 offset:1024
	ds_read_b128 v[152:155], v143 offset:2048
	ds_read_b128 v[156:159], v143 offset:3072
	v_add_u32_e32 v143, s91, v160
	ds_read_b128 v[166:169], v143
	ds_read_b128 v[170:173], v143 offset:1024
	ds_read_b128 v[174:177], v143 offset:2048
	ds_read_b128 v[182:185], v143 offset:3072
	ds_read_b128 v[188:191], v163 offset:32768
	ds_read_b128 v[192:195], v163 offset:33792
	ds_read_b128 v[196:199], v163 offset:34816
	ds_read_b128 v[200:203], v163 offset:35840
	ds_read_b128 v[204:207], v163 offset:36864
	ds_read_b128 v[208:211], v163 offset:37888
	ds_read_b128 v[212:215], v163 offset:38912
	ds_read_b128 v[216:219], v163 offset:39936
	s_waitcnt vmcnt(8)
	s_waitcnt lgkmcnt(0)
	s_barrier
	s_setprio 1
	s_waitcnt lgkmcnt(0)
	v_mfma_f32_16x16x32_bf16 v[126:129], v[130:133], v[188:191], v[126:129]
	v_mfma_f32_16x16x32_bf16 v[126:129], v[134:137], v[192:195], v[126:129]
	v_mfma_f32_16x16x32_bf16 v[122:125], v[156:159], v[192:195], v[122:125]
	v_mfma_f32_16x16x32_bf16 v[122:125], v[152:155], v[188:191], v[122:125]
	v_mfma_f32_16x16x32_bf16 v[106:109], v[152:155], v[196:199], v[106:109]
	v_mfma_f32_16x16x32_bf16 v[106:109], v[156:159], v[200:203], v[106:109]
	v_mfma_f32_16x16x32_bf16 v[110:113], v[134:137], v[200:203], v[110:113]
	v_mfma_f32_16x16x32_bf16 v[110:113], v[130:133], v[196:199], v[110:113]
	v_mfma_f32_16x16x32_bf16 v[94:97], v[130:133], v[204:207], v[94:97]
	v_mfma_f32_16x16x32_bf16 v[94:97], v[134:137], v[208:211], v[94:97]
	v_mfma_f32_16x16x32_bf16 v[90:93], v[156:159], v[208:211], v[90:93]
	v_mfma_f32_16x16x32_bf16 v[90:93], v[152:155], v[204:207], v[90:93]
	v_mfma_f32_16x16x32_bf16 v[74:77], v[152:155], v[212:215], v[74:77]
	v_mfma_f32_16x16x32_bf16 v[74:77], v[156:159], v[216:219], v[74:77]
	v_mfma_f32_16x16x32_bf16 v[78:81], v[134:137], v[216:219], v[78:81]
	v_mfma_f32_16x16x32_bf16 v[78:81], v[130:133], v[212:215], v[78:81]
	s_setprio 0
	s_setprio 1
	v_mfma_f32_16x16x32_bf16 v[70:73], v[166:169], v[212:215], v[70:73]
	v_mfma_f32_16x16x32_bf16 v[70:73], v[170:173], v[216:219], v[70:73]
	v_mfma_f32_16x16x32_bf16 v[66:69], v[182:185], v[216:219], v[66:69]
	v_mfma_f32_16x16x32_bf16 v[66:69], v[174:177], v[212:215], v[66:69]
	v_mfma_f32_16x16x32_bf16 v[82:85], v[174:177], v[204:207], v[82:85]
	v_mfma_f32_16x16x32_bf16 v[82:85], v[182:185], v[208:211], v[82:85]
	v_mfma_f32_16x16x32_bf16 v[86:89], v[170:173], v[208:211], v[86:89]
	v_mfma_f32_16x16x32_bf16 v[86:89], v[166:169], v[204:207], v[86:89]
	v_mfma_f32_16x16x32_bf16 v[102:105], v[166:169], v[196:199], v[102:105]
	v_mfma_f32_16x16x32_bf16 v[102:105], v[170:173], v[200:203], v[102:105]
	v_mfma_f32_16x16x32_bf16 v[98:101], v[182:185], v[200:203], v[98:101]
	v_mfma_f32_16x16x32_bf16 v[98:101], v[174:177], v[196:199], v[98:101]
	v_mfma_f32_16x16x32_bf16 v[114:117], v[174:177], v[188:191], v[114:117]
	v_mfma_f32_16x16x32_bf16 v[114:117], v[182:185], v[192:195], v[114:117]
	v_mfma_f32_16x16x32_bf16 v[118:121], v[170:173], v[192:195], v[118:121]
	v_mfma_f32_16x16x32_bf16 v[118:121], v[166:169], v[188:191], v[118:121]
	s_setprio 0
	s_barrier
; #define PG8_STAGE(bufoff, gbase, voff) do { _Pragma("unroll") for (int _i = 0; _i < 2; ++_i) \
;         __builtin_amdgcn_global_load_lds((const unsigned*)((const char*)(gbase) + (voff)[_i]), (PG8_LAS unsigned*)(lds + (bufoff) + ldsw + _i * 8192), 16, 0, 0); } while (0)
; #define PG8_LDA(dst, b, h) do { _Pragma("unroll") for (int m = 0; m < 4; ++m) _Pragma("unroll") for (int k = 0; k < 2; ++k) dst[m][k] = *(const PG8_LAS bf16x8*)(lds + PG8_SA(b, h) + aoff + m * 2048 + k * 1024); } while (0)
; #define PG8_LDB(dst, b, h) do { _Pragma("unroll") for (int n = 0; n < 2; ++n) _Pragma("unroll") for (int k = 0; k < 2; ++k) dst[n][k] = *(const PG8_LAS bf16x8*)(lds + PG8_SB(b, h) + boff + n * 2048 + k * 1024); } while (0)
; #define PG8_MMA(ai, bj, At, Bt) do { __builtin_amdgcn_s_setprio(1); _Pragma("unroll") for (int m = 0; m < 4; ++m) _Pragma("unroll") for (int n = 0; n < 2; ++n) _Pragma("unroll") for (int k = 0; k < 2; ++k) \
;         acc[ai][bj][m][n] = __builtin_amdgcn_mfma_f32_16x16x32_bf16(Bt[n][k], At[m][k], acc[ai][bj][m][n], 0, 0, 0); __builtin_amdgcn_s_setprio(0); } while (0)
; #define PG8_WAIT_V(n) asm volatile("s_waitcnt vmcnt(" #n ")" ::: "memory")
; #define PG8_BAR __builtin_amdgcn_s_barrier()
; template <class Epi, class Sched, bool ALIGN_EPI = false, bool SP2 = false, bool RS = false, bool BPRE = false>
; __device__ __forceinline__ void gemm_phase(PG8_LAS unsigned char* lds, const Gemm g, const Sched& S, const Epi& E, const float* rs_ss = nullptr, PG8_LAS float* rs_tab = nullptr) {
;     ...
;             const char* a1 = cA + (size_t)(t + 1) * kstep;
;             const char* a2 = last ? nA : cA + (size_t)(t + 2) * kstep; const char* b2 = last ? nB : cB + (size_t)(t + 2) * kstep;
;             const char* a3 = a2 + kstep; const char* b3 = b2 + kstep;
;             if (last && has_next) S.a_ready(nxt);
;             if constexpr (SP2) {
;             PG8_LDB(B0, 0, 0); PG8_LDB(B1, 0, 1); PG8_SCHED; PG8_LDA(At, 0, 0); PG8_STAGE(PG8_SA(1, 1), a1 + hstep, voffA);
;             PG8_WAIT_V(8); PG8_WAIT_L(0); PG8_BAR; PG8_MMA(0, 0, At, B0); PG8_MMA(0, 1, At, B1); PG8_BAR; PG8_SCHED;
;     ...
;             PG8_LDA(At, 1, 1); PG8_STAGE(PG8_SB(1, 0), b3, voffB); PG8_STAGE(PG8_SB(1, 1), b3 + hstep, voffB); PG8_STAGE(PG8_SA(1, 0), a3, voffA);
;             PG8_WAIT_V(8); PG8_WAIT_L(0); PG8_BAR; PG8_MMA(1, 0, At, B0); PG8_MMA(1, 1, At, B1); PG8_BAR; PG8_SCHED;
	s_add_u32 s70, s60, 0x4000
	s_addc_u32 s71, s61, 0
	s_add_i32 s90, s90, s15
	v_lshl_add_u64 v[178:179], s[70:71], 0, v[138:139]
	s_mov_b32 m0, s90
	s_nop 0
	global_load_lds_dwordx4 v[178:179], off
	s_add_i32 m0, s90, 0x2000
	s_add_u32 s60, s60, 0x84000
	v_lshl_add_u64 v[178:179], s[70:71], 0, v[140:141]
	s_addc_u32 s61, s61, 0
	s_add_i32 s70, s91, s15
	global_load_lds_dwordx4 v[178:179], off
	v_lshl_add_u64 v[178:179], s[60:61], 0, v[138:139]
	s_mov_b32 m0, s70
	s_nop 0
	global_load_lds_dwordx4 v[178:179], off
	v_lshl_add_u64 v[178:179], s[60:61], 0, v[140:141]
	s_add_i32 m0, s70, 0x2000
	s_nop 0
	global_load_lds_dwordx4 v[178:179], off
	v_lshl_add_u64 v[178:179], s[58:59], 0, v[138:139]
	s_mov_b32 m0, s79
	s_nop 0
	global_load_lds_dwordx4 v[178:179], off
	v_lshl_add_u64 v[178:179], s[58:59], 0, v[140:141]
	s_mov_b32 m0, s80
	s_nop 0
	global_load_lds_dwordx4 v[178:179], off
	ds_read_b128 v[188:191], v163 offset:49152
	ds_read_b128 v[192:195], v163 offset:50176
	ds_read_b128 v[196:199], v163 offset:51200
	ds_read_b128 v[200:203], v163 offset:52224
	ds_read_b128 v[204:207], v163 offset:53248
	ds_read_b128 v[208:211], v163 offset:54272
	ds_read_b128 v[212:215], v163 offset:55296
	ds_read_b128 v[216:219], v163 offset:56320
	s_waitcnt vmcnt(8)
	s_waitcnt lgkmcnt(0)
	s_barrier
	s_setprio 1
	s_waitcnt lgkmcnt(0)
	v_mfma_f32_16x16x32_bf16 v[62:65], v[130:133], v[188:191], v[62:65]
	v_mfma_f32_16x16x32_bf16 v[62:65], v[134:137], v[192:195], v[62:65]
	v_mfma_f32_16x16x32_bf16 v[58:61], v[156:159], v[192:195], v[58:61]
	v_mfma_f32_16x16x32_bf16 v[58:61], v[152:155], v[188:191], v[58:61]
	v_mfma_f32_16x16x32_bf16 v[42:45], v[152:155], v[196:199], v[42:45]
	v_mfma_f32_16x16x32_bf16 v[42:45], v[156:159], v[200:203], v[42:45]
	v_mfma_f32_16x16x32_bf16 v[46:49], v[134:137], v[200:203], v[46:49]
	v_mfma_f32_16x16x32_bf16 v[46:49], v[130:133], v[196:199], v[46:49]
	v_mfma_f32_16x16x32_bf16 v[30:33], v[130:133], v[204:207], v[30:33]
	v_mfma_f32_16x16x32_bf16 v[30:33], v[134:137], v[208:211], v[30:33]
	v_mfma_f32_16x16x32_bf16 v[26:29], v[156:159], v[208:211], v[26:29]
	v_mfma_f32_16x16x32_bf16 v[26:29], v[152:155], v[204:207], v[26:29]
	v_mfma_f32_16x16x32_bf16 v[10:13], v[152:155], v[212:215], v[10:13]
	v_mfma_f32_16x16x32_bf16 v[10:13], v[156:159], v[216:219], v[10:13]
	v_mfma_f32_16x16x32_bf16 v[14:17], v[134:137], v[216:219], v[14:17]
	v_mfma_f32_16x16x32_bf16 v[14:17], v[130:133], v[212:215], v[14:17]
	s_setprio 0
	s_setprio 1
	v_mfma_f32_16x16x32_bf16 v[6:9], v[166:169], v[212:215], v[6:9]
	v_mfma_f32_16x16x32_bf16 v[6:9], v[170:173], v[216:219], v[6:9]
	v_mfma_f32_16x16x32_bf16 v[2:5], v[182:185], v[216:219], v[2:5]
	v_mfma_f32_16x16x32_bf16 v[2:5], v[174:177], v[212:215], v[2:5]
	v_mfma_f32_16x16x32_bf16 v[18:21], v[174:177], v[204:207], v[18:21]
	v_mfma_f32_16x16x32_bf16 v[18:21], v[182:185], v[208:211], v[18:21]
	v_mfma_f32_16x16x32_bf16 v[22:25], v[170:173], v[208:211], v[22:25]
	v_mfma_f32_16x16x32_bf16 v[22:25], v[166:169], v[204:207], v[22:25]
	v_mfma_f32_16x16x32_bf16 v[38:41], v[166:169], v[196:199], v[38:41]
	v_mfma_f32_16x16x32_bf16 v[38:41], v[170:173], v[200:203], v[38:41]
	v_mfma_f32_16x16x32_bf16 v[34:37], v[182:185], v[200:203], v[34:37]
	v_mfma_f32_16x16x32_bf16 v[34:37], v[174:177], v[196:199], v[34:37]
	v_mfma_f32_16x16x32_bf16 v[50:53], v[174:177], v[188:191], v[50:53]
	v_mfma_f32_16x16x32_bf16 v[50:53], v[182:185], v[192:195], v[50:53]
	v_mfma_f32_16x16x32_bf16 v[54:57], v[170:173], v[192:195], v[54:57]
	v_mfma_f32_16x16x32_bf16 v[54:57], v[166:169], v[188:191], v[54:57]
	s_setprio 0
	s_barrier
	s_add_i32 s89, s89, 2
	s_add_u32 s56, s56, 0x8000
	s_addc_u32 s57, s57, 0
	s_add_u32 s87, s87, 0x8000
	s_addc_u32 s88, s88, 0
.LBB0_196:
	s_add_u32 s58, s56, 0xfff84000
	s_addc_u32 s59, s57, -1
	s_cmp_eq_u32 s89, 28
	s_cselect_b32 s70, s19, s58
	s_cselect_b32 s71, s5, s59
	s_cselect_b32 s60, s47, s87
	s_cselect_b32 s61, s17, s88
	s_add_u32 s58, s70, 0x4000
	s_addc_u32 s59, s71, 0
	v_lshl_add_u64 v[178:179], s[56:57], 0, v[138:139]
	s_add_i32 m0, s72, 0xc000
	s_nop 0
	global_load_lds_dwordx4 v[178:179], off
	v_lshl_add_u64 v[178:179], s[56:57], 0, v[146:147]
	s_add_i32 m0, s72, 0xe000
	s_nop 0
	global_load_lds_dwordx4 v[178:179], off
	ds_read_b128 v[130:133], v161
	ds_read_b128 v[134:137], v161 offset:1024
	ds_read_b128 v[152:155], v161 offset:2048
	ds_read_b128 v[156:159], v161 offset:3072
	ds_read_b128 v[166:169], v162
	ds_read_b128 v[170:173], v162 offset:1024
	ds_read_b128 v[174:177], v162 offset:2048
	ds_read_b128 v[182:185], v162 offset:3072
	ds_read_b128 v[188:191], v163
	ds_read_b128 v[192:195], v163 offset:1024
	ds_read_b128 v[196:199], v163 offset:2048
	ds_read_b128 v[200:203], v163 offset:3072
	ds_read_b128 v[204:207], v163 offset:4096
	ds_read_b128 v[208:211], v163 offset:5120
	ds_read_b128 v[212:215], v163 offset:6144
	ds_read_b128 v[216:219], v163 offset:7168
	s_waitcnt vmcnt(8)
	s_waitcnt lgkmcnt(0)
	s_barrier
; #define PG8_STAGE(bufoff, gbase, voff) do { _Pragma("unroll") for (int _i = 0; _i < 2; ++_i) \
;         __builtin_amdgcn_global_load_lds((const unsigned*)((const char*)(gbase) + (voff)[_i]), (PG8_LAS unsigned*)(lds + (bufoff) + ldsw + _i * 8192), 16, 0, 0); } while (0)
; #define PG8_LDA(dst, b, h) do { _Pragma("unroll") for (int m = 0; m < 4; ++m) _Pragma("unroll") for (int k = 0; k < 2; ++k) dst[m][k] = *(const PG8_LAS bf16x8*)(lds + PG8_SA(b, h) + aoff + m * 2048 + k * 1024); } while (0)
; #define PG8_LDB(dst, b, h) do { _Pragma("unroll") for (int n = 0; n < 2; ++n) _Pragma("unroll") for (int k = 0; k < 2; ++k) dst[n][k] = *(const PG8_LAS bf16x8*)(lds + PG8_SB(b, h) + boff + n * 2048 + k * 1024); } while (0)
; #define PG8_MMA(ai, bj, At, Bt) do { __builtin_amdgcn_s_setprio(1); _Pragma("unroll") for (int m = 0; m < 4; ++m) _Pragma("unroll") for (int n = 0; n < 2; ++n) _Pragma("unroll") for (int k = 0; k < 2; ++k) \
;         acc[ai][bj][m][n] = __builtin_amdgcn_mfma_f32_16x16x32_bf16(Bt[n][k], At[m][k], acc[ai][bj][m][n], 0, 0, 0); __builtin_amdgcn_s_setprio(0); } while (0)
; #define PG8_WAIT_V(n) asm volatile("s_waitcnt vmcnt(" #n ")" ::: "memory")
; #define PG8_WAIT_L(n) asm volatile("s_waitcnt lgkmcnt(" #n ")" ::: "memory")
; #define PG8_BAR __builtin_amdgcn_s_barrier()
; #define PG8_SCHED __builtin_amdgcn_sched_barrier(0)
; template <class Epi, class Sched, bool ALIGN_EPI = false, bool SP2 = false, bool RS = false, bool BPRE = false>
; __device__ __forceinline__ void gemm_phase(PG8_LAS unsigned char* lds, const Gemm g, const Sched& S, const Epi& E, const float* rs_ss = nullptr, PG8_LAS float* rs_tab = nullptr) {
;     ...
;             PG8_WAIT_V(8); PG8_WAIT_L(0); PG8_BAR; PG8_MMA(0, 0, At, B0); PG8_MMA(0, 1, At, B1); PG8_BAR; PG8_SCHED;
;             PG8_LDA(At, 0, 1); PG8_STAGE(PG8_SB(0, 0), b2, voffB); PG8_STAGE(PG8_SB(0, 1), b2 + hstep, voffB); PG8_STAGE(PG8_SA(0, 0), a2, voffA);
;             PG8_WAIT_V(8); PG8_WAIT_L(0); PG8_BAR; PG8_MMA(1, 0, At, B0); PG8_MMA(1, 1, At, B1); PG8_BAR; PG8_SCHED;
;             PG8_LDB(B0, 1, 0); PG8_LDB(B1, 1, 1); PG8_SCHED; PG8_LDA(At, 1, 0); PG8_STAGE(PG8_SA(0, 1), a2 + hstep, voffA);
;             PG8_WAIT_V(8); PG8_WAIT_L(0); PG8_BAR; PG8_MMA(0, 0, At, B0); PG8_MMA(0, 1, At, B1); PG8_BAR; PG8_SCHED;
	s_setprio 1
	s_waitcnt lgkmcnt(0)
	v_mfma_f32_16x16x32_bf16 v[126:129], v[130:133], v[188:191], v[126:129]
	v_mfma_f32_16x16x32_bf16 v[126:129], v[134:137], v[192:195], v[126:129]
	v_mfma_f32_16x16x32_bf16 v[122:125], v[156:159], v[192:195], v[122:125]
	v_mfma_f32_16x16x32_bf16 v[122:125], v[152:155], v[188:191], v[122:125]
	v_mfma_f32_16x16x32_bf16 v[106:109], v[152:155], v[196:199], v[106:109]
	v_mfma_f32_16x16x32_bf16 v[106:109], v[156:159], v[200:203], v[106:109]
	v_mfma_f32_16x16x32_bf16 v[110:113], v[134:137], v[200:203], v[110:113]
	v_mfma_f32_16x16x32_bf16 v[110:113], v[130:133], v[196:199], v[110:113]
	v_mfma_f32_16x16x32_bf16 v[94:97], v[130:133], v[204:207], v[94:97]
	v_mfma_f32_16x16x32_bf16 v[94:97], v[134:137], v[208:211], v[94:97]
	v_mfma_f32_16x16x32_bf16 v[90:93], v[156:159], v[208:211], v[90:93]
	v_mfma_f32_16x16x32_bf16 v[90:93], v[152:155], v[204:207], v[90:93]
	v_mfma_f32_16x16x32_bf16 v[74:77], v[152:155], v[212:215], v[74:77]
	v_mfma_f32_16x16x32_bf16 v[74:77], v[156:159], v[216:219], v[74:77]
	v_mfma_f32_16x16x32_bf16 v[78:81], v[134:137], v[216:219], v[78:81]
	v_mfma_f32_16x16x32_bf16 v[78:81], v[130:133], v[212:215], v[78:81]
	s_setprio 0
	s_setprio 1
	v_mfma_f32_16x16x32_bf16 v[70:73], v[166:169], v[212:215], v[70:73]
	v_mfma_f32_16x16x32_bf16 v[70:73], v[170:173], v[216:219], v[70:73]
	v_mfma_f32_16x16x32_bf16 v[66:69], v[182:185], v[216:219], v[66:69]
	v_mfma_f32_16x16x32_bf16 v[66:69], v[174:177], v[212:215], v[66:69]
	v_mfma_f32_16x16x32_bf16 v[82:85], v[174:177], v[204:207], v[82:85]
	v_mfma_f32_16x16x32_bf16 v[82:85], v[182:185], v[208:211], v[82:85]
	v_mfma_f32_16x16x32_bf16 v[86:89], v[170:173], v[208:211], v[86:89]
	v_mfma_f32_16x16x32_bf16 v[86:89], v[166:169], v[204:207], v[86:89]
	v_mfma_f32_16x16x32_bf16 v[102:105], v[166:169], v[196:199], v[102:105]
	v_mfma_f32_16x16x32_bf16 v[102:105], v[170:173], v[200:203], v[102:105]
	v_mfma_f32_16x16x32_bf16 v[98:101], v[182:185], v[200:203], v[98:101]
	v_mfma_f32_16x16x32_bf16 v[98:101], v[174:177], v[196:199], v[98:101]
	v_mfma_f32_16x16x32_bf16 v[114:117], v[174:177], v[188:191], v[114:117]
	v_mfma_f32_16x16x32_bf16 v[114:117], v[182:185], v[192:195], v[114:117]
	v_mfma_f32_16x16x32_bf16 v[118:121], v[170:173], v[192:195], v[118:121]
	v_mfma_f32_16x16x32_bf16 v[118:121], v[166:169], v[188:191], v[118:121]
	s_setprio 0
	s_barrier
	s_add_i32 s90, s83, s15
	v_lshl_add_u64 v[178:179], s[60:61], 0, v[138:139]
	s_mov_b32 m0, s90
	s_nop 0
	global_load_lds_dwordx4 v[178:179], off
	s_add_i32 m0, s90, 0x2000
	s_add_u32 s90, s60, 0x80000
	v_lshl_add_u64 v[178:179], s[60:61], 0, v[140:141]
	s_addc_u32 s91, s61, 0
	s_add_i32 s92, s86, s15
	global_load_lds_dwordx4 v[178:179], off
	v_lshl_add_u64 v[178:179], s[90:91], 0, v[138:139]
	s_mov_b32 m0, s92
	s_nop 0
	global_load_lds_dwordx4 v[178:179], off
	v_lshl_add_u64 v[178:179], s[90:91], 0, v[140:141]
	s_add_i32 m0, s92, 0x2000
	s_nop 0
	global_load_lds_dwordx4 v[178:179], off
	v_lshl_add_u64 v[178:179], s[70:71], 0, v[138:139]
	s_mov_b32 m0, s72
	s_nop 0
	global_load_lds_dwordx4 v[178:179], off
	v_lshl_add_u64 v[178:179], s[70:71], 0, v[140:141]
	s_mov_b32 m0, s73
	s_nop 0
	global_load_lds_dwordx4 v[178:179], off
	ds_read_b128 v[188:191], v163 offset:16384
	ds_read_b128 v[192:195], v163 offset:17408
	ds_read_b128 v[196:199], v163 offset:18432
	ds_read_b128 v[200:203], v163 offset:19456
	ds_read_b128 v[204:207], v163 offset:20480
	ds_read_b128 v[208:211], v163 offset:21504
	ds_read_b128 v[212:215], v163 offset:22528
	ds_read_b128 v[216:219], v163 offset:23552
	s_waitcnt vmcnt(8)
	s_waitcnt lgkmcnt(0)
	s_barrier
	s_setprio 1
	s_waitcnt lgkmcnt(0)
	v_mfma_f32_16x16x32_bf16 v[62:65], v[130:133], v[188:191], v[62:65]
	v_mfma_f32_16x16x32_bf16 v[62:65], v[134:137], v[192:195], v[62:65]
	v_mfma_f32_16x16x32_bf16 v[58:61], v[156:159], v[192:195], v[58:61]
	v_mfma_f32_16x16x32_bf16 v[58:61], v[152:155], v[188:191], v[58:61]
	v_mfma_f32_16x16x32_bf16 v[42:45], v[152:155], v[196:199], v[42:45]
	v_mfma_f32_16x16x32_bf16 v[42:45], v[156:159], v[200:203], v[42:45]
	v_mfma_f32_16x16x32_bf16 v[46:49], v[134:137], v[200:203], v[46:49]
	v_mfma_f32_16x16x32_bf16 v[46:49], v[130:133], v[196:199], v[46:49]
	v_mfma_f32_16x16x32_bf16 v[30:33], v[130:133], v[204:207], v[30:33]
	v_mfma_f32_16x16x32_bf16 v[30:33], v[134:137], v[208:211], v[30:33]
	v_mfma_f32_16x16x32_bf16 v[26:29], v[156:159], v[208:211], v[26:29]
	v_mfma_f32_16x16x32_bf16 v[26:29], v[152:155], v[204:207], v[26:29]
	v_mfma_f32_16x16x32_bf16 v[10:13], v[152:155], v[212:215], v[10:13]
	v_mfma_f32_16x16x32_bf16 v[10:13], v[156:159], v[216:219], v[10:13]
	v_mfma_f32_16x16x32_bf16 v[14:17], v[134:137], v[216:219], v[14:17]
	v_mfma_f32_16x16x32_bf16 v[14:17], v[130:133], v[212:215], v[14:17]
	s_setprio 0
	s_setprio 1
	v_mfma_f32_16x16x32_bf16 v[6:9], v[166:169], v[212:215], v[6:9]
	v_mfma_f32_16x16x32_bf16 v[6:9], v[170:173], v[216:219], v[6:9]
	v_mfma_f32_16x16x32_bf16 v[2:5], v[182:185], v[216:219], v[2:5]
	v_mfma_f32_16x16x32_bf16 v[2:5], v[174:177], v[212:215], v[2:5]
	v_mfma_f32_16x16x32_bf16 v[18:21], v[174:177], v[204:207], v[18:21]
	v_mfma_f32_16x16x32_bf16 v[18:21], v[182:185], v[208:211], v[18:21]
	v_mfma_f32_16x16x32_bf16 v[22:25], v[170:173], v[208:211], v[22:25]
	v_mfma_f32_16x16x32_bf16 v[22:25], v[166:169], v[204:207], v[22:25]
	v_mfma_f32_16x16x32_bf16 v[38:41], v[166:169], v[196:199], v[38:41]
	v_mfma_f32_16x16x32_bf16 v[38:41], v[170:173], v[200:203], v[38:41]
	v_mfma_f32_16x16x32_bf16 v[34:37], v[182:185], v[200:203], v[34:37]
	v_mfma_f32_16x16x32_bf16 v[34:37], v[174:177], v[196:199], v[34:37]
	v_mfma_f32_16x16x32_bf16 v[50:53], v[174:177], v[188:191], v[50:53]
	v_mfma_f32_16x16x32_bf16 v[50:53], v[182:185], v[192:195], v[50:53]
	v_mfma_f32_16x16x32_bf16 v[54:57], v[170:173], v[192:195], v[54:57]
	v_mfma_f32_16x16x32_bf16 v[54:57], v[166:169], v[188:191], v[54:57]
	s_setprio 0
	s_barrier
; #define PG8_STAGE(bufoff, gbase, voff) do { _Pragma("unroll") for (int _i = 0; _i < 2; ++_i) \
;         __builtin_amdgcn_global_load_lds((const unsigned*)((const char*)(gbase) + (voff)[_i]), (PG8_LAS unsigned*)(lds + (bufoff) + ldsw + _i * 8192), 16, 0, 0); } while (0)
; #define PG8_LDA(dst, b, h) do { _Pragma("unroll") for (int m = 0; m < 4; ++m) _Pragma("unroll") for (int k = 0; k < 2; ++k) dst[m][k] = *(const PG8_LAS bf16x8*)(lds + PG8_SA(b, h) + aoff + m * 2048 + k * 1024); } while (0)
; #define PG8_LDB(dst, b, h) do { _Pragma("unroll") for (int n = 0; n < 2; ++n) _Pragma("unroll") for (int k = 0; k < 2; ++k) dst[n][k] = *(const PG8_LAS bf16x8*)(lds + PG8_SB(b, h) + boff + n * 2048 + k * 1024); } while (0)
; #define PG8_MMA(ai, bj, At, Bt) do { __builtin_amdgcn_s_setprio(1); _Pragma("unroll") for (int m = 0; m < 4; ++m) _Pragma("unroll") for (int n = 0; n < 2; ++n) _Pragma("unroll") for (int k = 0; k < 2; ++k) \
;         acc[ai][bj][m][n] = __builtin_amdgcn_mfma_f32_16x16x32_bf16(Bt[n][k], At[m][k], acc[ai][bj][m][n], 0, 0, 0); __builtin_amdgcn_s_setprio(0); } while (0)
; #define PG8_WAIT_V(n) asm volatile("s_waitcnt vmcnt(" #n ")" ::: "memory")
; #define PG8_WAIT_L(n) asm volatile("s_waitcnt lgkmcnt(" #n ")" ::: "memory")
; #define PG8_BAR __builtin_amdgcn_s_barrier()
; #define PG8_SCHED __builtin_amdgcn_sched_barrier(0)
; template <class Epi, class Sched, bool ALIGN_EPI = false, bool SP2 = false, bool RS = false, bool BPRE = false>
; __device__ __forceinline__ void gemm_phase(PG8_LAS unsigned char* lds, const Gemm g, const Sched& S, const Epi& E, const float* rs_ss = nullptr, PG8_LAS float* rs_tab = nullptr) {
;     ...
;             PG8_LDB(B0, 1, 0); PG8_LDB(B1, 1, 1); PG8_SCHED; PG8_LDA(At, 1, 0); PG8_STAGE(PG8_SA(0, 1), a2 + hstep, voffA);
;             PG8_WAIT_V(8); PG8_WAIT_L(0); PG8_BAR; PG8_MMA(0, 0, At, B0); PG8_MMA(0, 1, At, B1); PG8_BAR; PG8_SCHED;
;             PG8_LDA(At, 1, 1); PG8_STAGE(PG8_SB(1, 0), b3, voffB); PG8_STAGE(PG8_SB(1, 1), b3 + hstep, voffB); PG8_STAGE(PG8_SA(1, 0), a3, voffA);
;             PG8_WAIT_V(8); PG8_WAIT_L(0); PG8_BAR; PG8_MMA(1, 0, At, B0); PG8_MMA(1, 1, At, B1); PG8_BAR; PG8_SCHED;
	s_add_u32 s70, s70, 0x80000
	s_addc_u32 s71, s71, 0
	s_mov_b32 m0, s74
	v_lshl_add_u64 v[178:179], s[70:71], 0, v[138:139]
	global_load_lds_dwordx4 v[178:179], off
	v_lshl_add_u64 v[178:179], s[70:71], 0, v[140:141]
	s_mov_b32 m0, s75
	s_nop 0
	global_load_lds_dwordx4 v[178:179], off
	s_add_i32 s90, 0, 0x18000
	v_add_u32_e32 v143, s90, v160
	s_add_i32 s91, 0, 0x1c000
	ds_read_b128 v[130:133], v143
	ds_read_b128 v[134:137], v143 offset:1024
	ds_read_b128 v[152:155], v143 offset:2048
	ds_read_b128 v[156:159], v143 offset:3072
	v_add_u32_e32 v143, s91, v160
	ds_read_b128 v[166:169], v143
	ds_read_b128 v[170:173], v143 offset:1024
	ds_read_b128 v[174:177], v143 offset:2048
	ds_read_b128 v[182:185], v143 offset:3072
	ds_read_b128 v[188:191], v163 offset:32768
	ds_read_b128 v[192:195], v163 offset:33792
	ds_read_b128 v[196:199], v163 offset:34816
	ds_read_b128 v[200:203], v163 offset:35840
	ds_read_b128 v[204:207], v163 offset:36864
	ds_read_b128 v[208:211], v163 offset:37888
	ds_read_b128 v[212:215], v163 offset:38912
	ds_read_b128 v[216:219], v163 offset:39936
	s_waitcnt vmcnt(8)
	s_waitcnt lgkmcnt(0)
	s_barrier
	s_setprio 1
	s_waitcnt lgkmcnt(0)
	v_mfma_f32_16x16x32_bf16 v[126:129], v[130:133], v[188:191], v[126:129]
	v_mfma_f32_16x16x32_bf16 v[126:129], v[134:137], v[192:195], v[126:129]
	v_mfma_f32_16x16x32_bf16 v[122:125], v[156:159], v[192:195], v[122:125]
	v_mfma_f32_16x16x32_bf16 v[122:125], v[152:155], v[188:191], v[122:125]
	v_mfma_f32_16x16x32_bf16 v[106:109], v[152:155], v[196:199], v[106:109]
	v_mfma_f32_16x16x32_bf16 v[106:109], v[156:159], v[200:203], v[106:109]
	v_mfma_f32_16x16x32_bf16 v[110:113], v[134:137], v[200:203], v[110:113]
	v_mfma_f32_16x16x32_bf16 v[110:113], v[130:133], v[196:199], v[110:113]
	v_mfma_f32_16x16x32_bf16 v[94:97], v[130:133], v[204:207], v[94:97]
	v_mfma_f32_16x16x32_bf16 v[94:97], v[134:137], v[208:211], v[94:97]
	v_mfma_f32_16x16x32_bf16 v[90:93], v[156:159], v[208:211], v[90:93]
	v_mfma_f32_16x16x32_bf16 v[90:93], v[152:155], v[204:207], v[90:93]
	v_mfma_f32_16x16x32_bf16 v[74:77], v[152:155], v[212:215], v[74:77]
	v_mfma_f32_16x16x32_bf16 v[74:77], v[156:159], v[216:219], v[74:77]
	v_mfma_f32_16x16x32_bf16 v[78:81], v[134:137], v[216:219], v[78:81]
	v_mfma_f32_16x16x32_bf16 v[78:81], v[130:133], v[212:215], v[78:81]
	s_setprio 0
	s_setprio 1
	v_mfma_f32_16x16x32_bf16 v[70:73], v[166:169], v[212:215], v[70:73]
	v_mfma_f32_16x16x32_bf16 v[70:73], v[170:173], v[216:219], v[70:73]
	v_mfma_f32_16x16x32_bf16 v[66:69], v[182:185], v[216:219], v[66:69]
	v_mfma_f32_16x16x32_bf16 v[66:69], v[174:177], v[212:215], v[66:69]
	v_mfma_f32_16x16x32_bf16 v[82:85], v[174:177], v[204:207], v[82:85]
	v_mfma_f32_16x16x32_bf16 v[82:85], v[182:185], v[208:211], v[82:85]
	v_mfma_f32_16x16x32_bf16 v[86:89], v[170:173], v[208:211], v[86:89]
	v_mfma_f32_16x16x32_bf16 v[86:89], v[166:169], v[204:207], v[86:89]
	v_mfma_f32_16x16x32_bf16 v[102:105], v[166:169], v[196:199], v[102:105]
	v_mfma_f32_16x16x32_bf16 v[102:105], v[170:173], v[200:203], v[102:105]
	v_mfma_f32_16x16x32_bf16 v[98:101], v[182:185], v[200:203], v[98:101]
	v_mfma_f32_16x16x32_bf16 v[98:101], v[174:177], v[196:199], v[98:101]
	v_mfma_f32_16x16x32_bf16 v[114:117], v[174:177], v[188:191], v[114:117]
	v_mfma_f32_16x16x32_bf16 v[114:117], v[182:185], v[192:195], v[114:117]
	v_mfma_f32_16x16x32_bf16 v[118:121], v[170:173], v[192:195], v[118:121]
	v_mfma_f32_16x16x32_bf16 v[118:121], v[166:169], v[188:191], v[118:121]
	s_setprio 0
	s_barrier
; #define PG8_STAGE(bufoff, gbase, voff) do { _Pragma("unroll") for (int _i = 0; _i < 2; ++_i) \
;         __builtin_amdgcn_global_load_lds((const unsigned*)((const char*)(gbase) + (voff)[_i]), (PG8_LAS unsigned*)(lds + (bufoff) + ldsw + _i * 8192), 16, 0, 0); } while (0)
; #define PG8_LDA(dst, b, h) do { _Pragma("unroll") for (int m = 0; m < 4; ++m) _Pragma("unroll") for (int k = 0; k < 2; ++k) dst[m][k] = *(const PG8_LAS bf16x8*)(lds + PG8_SA(b, h) + aoff + m * 2048 + k * 1024); } while (0)
; #define PG8_MMA(ai, bj, At, Bt) do { __builtin_amdgcn_s_setprio(1); _Pragma("unroll") for (int m = 0; m < 4; ++m) _Pragma("unroll") for (int n = 0; n < 2; ++n) _Pragma("unroll") for (int k = 0; k < 2; ++k) \
;         acc[ai][bj][m][n] = __builtin_amdgcn_mfma_f32_16x16x32_bf16(Bt[n][k], At[m][k], acc[ai][bj][m][n], 0, 0, 0); __builtin_amdgcn_s_setprio(0); } while (0)
; #define PG8_WAIT_V(n) asm volatile("s_waitcnt vmcnt(" #n ")" ::: "memory")
; #define PG8_WAIT_L(n) asm volatile("s_waitcnt lgkmcnt(" #n ")" ::: "memory")
; #define PG8_BAR __builtin_amdgcn_s_barrier()
; #define PG8_SCHED __builtin_amdgcn_sched_barrier(0)
; template <class Epi, class Sched, bool ALIGN_EPI = false, bool SP2 = false, bool RS = false, bool BPRE = false>
; __device__ __forceinline__ void gemm_phase(PG8_LAS unsigned char* lds, const Gemm g, const Sched& S, const Epi& E, const float* rs_ss = nullptr, PG8_LAS float* rs_tab = nullptr) {
;     ...
;             PG8_LDA(At, 1, 1); PG8_STAGE(PG8_SB(1, 0), b3, voffB); PG8_STAGE(PG8_SB(1, 1), b3 + hstep, voffB); PG8_STAGE(PG8_SA(1, 0), a3, voffA);
;             PG8_WAIT_V(8); PG8_WAIT_L(0); PG8_BAR; PG8_MMA(1, 0, At, B0); PG8_MMA(1, 1, At, B1); PG8_BAR; PG8_SCHED;
;     ...
;         if constexpr (ALIGN_EPI) { if (wr == 0) PG8_BAR; }
	s_add_u32 s70, s60, 0x4000
	s_addc_u32 s71, s61, 0
	s_add_i32 s90, s90, s15
	v_lshl_add_u64 v[178:179], s[70:71], 0, v[138:139]
	s_mov_b32 m0, s90
	s_nop 0
	global_load_lds_dwordx4 v[178:179], off
	s_add_i32 m0, s90, 0x2000
	s_add_u32 s60, s60, 0x84000
	v_lshl_add_u64 v[178:179], s[70:71], 0, v[140:141]
	s_addc_u32 s61, s61, 0
	s_add_i32 s70, s91, s15
	global_load_lds_dwordx4 v[178:179], off
	v_lshl_add_u64 v[178:179], s[60:61], 0, v[138:139]
	s_mov_b32 m0, s70
	s_nop 0
	global_load_lds_dwordx4 v[178:179], off
	v_lshl_add_u64 v[178:179], s[60:61], 0, v[140:141]
	s_add_i32 m0, s70, 0x2000
	s_nop 0
	global_load_lds_dwordx4 v[178:179], off
	v_lshl_add_u64 v[178:179], s[58:59], 0, v[138:139]
	s_mov_b32 m0, s79
	s_nop 0
	global_load_lds_dwordx4 v[178:179], off
	v_lshl_add_u64 v[178:179], s[58:59], 0, v[140:141]
	s_mov_b32 m0, s80
	s_nop 0
	global_load_lds_dwordx4 v[178:179], off
	ds_read_b128 v[188:191], v163 offset:49152
	ds_read_b128 v[192:195], v163 offset:50176
	ds_read_b128 v[196:199], v163 offset:51200
	ds_read_b128 v[200:203], v163 offset:52224
	ds_read_b128 v[204:207], v163 offset:53248
	ds_read_b128 v[208:211], v163 offset:54272
	ds_read_b128 v[212:215], v163 offset:55296
	ds_read_b128 v[216:219], v163 offset:56320
	s_waitcnt vmcnt(8)
	s_waitcnt lgkmcnt(0)
	s_barrier
	s_setprio 1
	s_waitcnt lgkmcnt(0)
	v_mfma_f32_16x16x32_bf16 v[62:65], v[130:133], v[188:191], v[62:65]
	v_mfma_f32_16x16x32_bf16 v[62:65], v[134:137], v[192:195], v[62:65]
	v_mfma_f32_16x16x32_bf16 v[58:61], v[156:159], v[192:195], v[58:61]
	v_mfma_f32_16x16x32_bf16 v[58:61], v[152:155], v[188:191], v[58:61]
	v_mfma_f32_16x16x32_bf16 v[42:45], v[152:155], v[196:199], v[42:45]
	v_mfma_f32_16x16x32_bf16 v[42:45], v[156:159], v[200:203], v[42:45]
	v_mfma_f32_16x16x32_bf16 v[46:49], v[134:137], v[200:203], v[46:49]
	v_mfma_f32_16x16x32_bf16 v[46:49], v[130:133], v[196:199], v[46:49]
	v_mfma_f32_16x16x32_bf16 v[30:33], v[130:133], v[204:207], v[30:33]
	v_mfma_f32_16x16x32_bf16 v[30:33], v[134:137], v[208:211], v[30:33]
	v_mfma_f32_16x16x32_bf16 v[26:29], v[156:159], v[208:211], v[26:29]
	v_mfma_f32_16x16x32_bf16 v[26:29], v[152:155], v[204:207], v[26:29]
	v_mfma_f32_16x16x32_bf16 v[10:13], v[152:155], v[212:215], v[10:13]
	v_mfma_f32_16x16x32_bf16 v[10:13], v[156:159], v[216:219], v[10:13]
	v_mfma_f32_16x16x32_bf16 v[14:17], v[134:137], v[216:219], v[14:17]
	v_mfma_f32_16x16x32_bf16 v[14:17], v[130:133], v[212:215], v[14:17]
	s_setprio 0
	s_setprio 1
	v_mfma_f32_16x16x32_bf16 v[6:9], v[166:169], v[212:215], v[6:9]
	v_mfma_f32_16x16x32_bf16 v[6:9], v[170:173], v[216:219], v[6:9]
	v_mfma_f32_16x16x32_bf16 v[2:5], v[182:185], v[216:219], v[2:5]
	v_mfma_f32_16x16x32_bf16 v[2:5], v[174:177], v[212:215], v[2:5]
	v_mfma_f32_16x16x32_bf16 v[18:21], v[174:177], v[204:207], v[18:21]
	v_mfma_f32_16x16x32_bf16 v[18:21], v[182:185], v[208:211], v[18:21]
	v_mfma_f32_16x16x32_bf16 v[22:25], v[170:173], v[208:211], v[22:25]
	v_mfma_f32_16x16x32_bf16 v[22:25], v[166:169], v[204:207], v[22:25]
	v_mfma_f32_16x16x32_bf16 v[38:41], v[166:169], v[196:199], v[38:41]
	v_mfma_f32_16x16x32_bf16 v[38:41], v[170:173], v[200:203], v[38:41]
	v_mfma_f32_16x16x32_bf16 v[34:37], v[182:185], v[200:203], v[34:37]
	v_mfma_f32_16x16x32_bf16 v[34:37], v[174:177], v[196:199], v[34:37]
	v_mfma_f32_16x16x32_bf16 v[50:53], v[174:177], v[188:191], v[50:53]
	v_mfma_f32_16x16x32_bf16 v[50:53], v[182:185], v[192:195], v[50:53]
	v_mfma_f32_16x16x32_bf16 v[54:57], v[170:173], v[192:195], v[54:57]
	v_mfma_f32_16x16x32_bf16 v[54:57], v[166:169], v[188:191], v[54:57]
	s_setprio 0
	s_barrier
	s_add_i32 s89, s89, 2
	s_add_u32 s56, s56, 0x8000
	s_addc_u32 s57, s57, 0
	s_add_u32 s87, s87, 0x8000
	s_addc_u32 s88, s88, 0
	s_cmp_gt_u32 s89, 29
	s_cbranch_scc0 .LBB0_196
	s_and_b64 vcc, exec, s[12:13]
	s_cbranch_vccz .LBB0_199
	s_barrier
